# phase_prep: first weight-transpose tile of each workgroup also loads its 8 rows + gains back to back
# baseline (speedup 1.0000x reference)
.LBB0_23:
	s_lshr_b32 s2, s12, 7
	v_cvt_f32_ubyte0_e32 v3, s2
	v_rcp_iflag_f32_e32 v3, v3
	s_sub_i32 s20, 0, s2
	s_abs_i32 s19, s3
	s_ashr_i32 s18, s3, 31
	v_mul_f32_e32 v3, 0x4f7ffffe, v3
	v_cvt_u32_f32_e32 v3, v3
	v_mbcnt_lo_u32_b32 v2, -1, v2
	v_mbcnt_hi_u32_b32 v39, -1, v2
	v_lshlrev_b32_e32 v2, 2, v39
	v_readfirstlane_b32 s21, v3
	s_mul_i32 s20, s20, s21
	s_mul_hi_u32 s20, s21, s20
	s_add_i32 s21, s21, s20
	s_mul_hi_u32 s20, s19, s21
	s_mul_i32 s21, s20, s2
	s_sub_i32 s19, s19, s21
	s_add_i32 s21, s20, 1
	s_sub_i32 s23, s19, s2
	s_cmp_ge_u32 s19, s2
	s_cselect_b32 s20, s21, s20
	s_cselect_b32 s19, s23, s19
	s_add_i32 s21, s20, 1
	s_cmp_ge_u32 s19, s2
	s_cselect_b32 s19, s21, s20
	s_xor_b32 s19, s19, s18
	s_sub_i32 s19, s19, s18
	s_mul_i32 s2, s19, s2
	s_sub_i32 s2, s3, s2
	v_add_u32_e32 v38, s85, v39
	s_lshl_b32 s18, s2, 7
	v_and_b32_e32 v41, 0x7c, v2
	v_ashrrev_i32_e32 v42, 5, v38
	v_or_b32_e32 v3, s18, v41
	v_lshl_add_u32 v36, s19, 7, v42
	s_ashr_i32 s19, s18, 31
	v_mov_b32_e32 v2, 0
	v_cmp_gt_i32_e32 vcc, s22, v3
	v_lshlrev_b32_e32 v34, 2, v41
	v_mov_b32_e32 v6, 0
	v_mov_b32_e32 v7, 0
	v_mov_b32_e32 v8, 0
	v_mov_b32_e32 v9, 0
	v_mov_b32_e32 v2, 0
	v_mov_b32_e32 v3, 0
	v_mov_b32_e32 v4, 0
	v_mov_b32_e32 v5, 0
	v_mov_b32_e32 v6, 0
	v_mov_b32_e32 v7, 0
	v_mov_b32_e32 v8, 0
	v_mov_b32_e32 v9, 0
	v_mov_b32_e32 v10, 0
	v_mov_b32_e32 v11, 0
	v_mov_b32_e32 v12, 0
	v_mov_b32_e32 v13, 0
	v_mov_b32_e32 v14, 0
	v_mov_b32_e32 v15, 0
	v_mov_b32_e32 v16, 0
	v_mov_b32_e32 v17, 0
	v_mov_b32_e32 v18, 0
	v_mov_b32_e32 v19, 0
	v_mov_b32_e32 v20, 0
	v_mov_b32_e32 v21, 0
	v_mov_b32_e32 v22, 0
	v_mov_b32_e32 v23, 0
	v_mov_b32_e32 v24, 0
	v_mov_b32_e32 v25, 0
	v_mov_b32_e32 v26, 0
	v_mov_b32_e32 v27, 0
	v_mov_b32_e32 v28, 0
	v_mov_b32_e32 v29, 0
	v_mov_b32_e32 v30, 0
	v_mov_b32_e32 v31, 0
	v_mov_b32_e32 v32, 0
	v_mov_b32_e32 v33, 0
	v_mov_b32_e32 v35, 0
	s_and_saveexec_b64 s[20:21], vcc
	s_cbranch_execz .LBB0_47
	v_mad_i64_i32 v[202:203], s[24:25], v36, s22, 0
	v_lshl_add_u64 v[202:203], v[202:203], 2, s[14:15]
	v_lshl_add_u64 v[202:203], s[18:19], 2, v[202:203]
	v_lshl_add_u64 v[202:203], v[202:203], 0, v[34:35]
	global_load_dwordx4 v[6:9], v[202:203], off
	v_add_u32_e32 v200, 16, v36
	v_mad_i64_i32 v[202:203], s[24:25], v200, s22, 0
	v_lshl_add_u64 v[202:203], v[202:203], 2, s[14:15]
	v_lshl_add_u64 v[202:203], s[18:19], 2, v[202:203]
	v_lshl_add_u64 v[202:203], v[202:203], 0, v[34:35]
	global_load_dwordx4 v[2:5], v[202:203], off
	v_add_u32_e32 v200, 32, v36
	v_mad_i64_i32 v[202:203], s[24:25], v200, s22, 0
	v_lshl_add_u64 v[202:203], v[202:203], 2, s[14:15]
	v_lshl_add_u64 v[202:203], s[18:19], 2, v[202:203]
	v_lshl_add_u64 v[202:203], v[202:203], 0, v[34:35]
	global_load_dwordx4 v[14:17], v[202:203], off
	v_add_u32_e32 v200, 48, v36
	v_mad_i64_i32 v[202:203], s[24:25], v200, s22, 0
	v_lshl_add_u64 v[202:203], v[202:203], 2, s[14:15]
	v_lshl_add_u64 v[202:203], s[18:19], 2, v[202:203]
	v_lshl_add_u64 v[202:203], v[202:203], 0, v[34:35]
	global_load_dwordx4 v[10:13], v[202:203], off
	v_add_u32_e32 v200, 64, v36
	v_mad_i64_i32 v[202:203], s[24:25], v200, s22, 0
	v_lshl_add_u64 v[202:203], v[202:203], 2, s[14:15]
	v_lshl_add_u64 v[202:203], s[18:19], 2, v[202:203]
	v_lshl_add_u64 v[202:203], v[202:203], 0, v[34:35]
	global_load_dwordx4 v[22:25], v[202:203], off
	v_add_u32_e32 v200, 80, v36
	v_mad_i64_i32 v[202:203], s[24:25], v200, s22, 0
	v_lshl_add_u64 v[202:203], v[202:203], 2, s[14:15]
	v_lshl_add_u64 v[202:203], s[18:19], 2, v[202:203]
	v_lshl_add_u64 v[202:203], v[202:203], 0, v[34:35]
	global_load_dwordx4 v[18:21], v[202:203], off
	v_add_u32_e32 v200, 96, v36
	v_mad_i64_i32 v[202:203], s[24:25], v200, s22, 0
	v_lshl_add_u64 v[202:203], v[202:203], 2, s[14:15]
	v_lshl_add_u64 v[202:203], s[18:19], 2, v[202:203]
	v_lshl_add_u64 v[202:203], v[202:203], 0, v[34:35]
	global_load_dwordx4 v[30:33], v[202:203], off
	v_add_u32_e32 v200, 112, v36
	v_mad_i64_i32 v[202:203], s[22:23], v200, s22, 0
	v_lshl_add_u64 v[202:203], v[202:203], 2, s[14:15]
	v_lshl_add_u64 v[202:203], s[18:19], 2, v[202:203]
	v_lshl_add_u64 v[202:203], v[202:203], 0, v[34:35]
	global_load_dwordx4 v[26:29], v[202:203], off
	s_cmp_eq_u64 s[16:17], 0
	s_cbranch_scc1 .LBB0_47
	v_ashrrev_i32_e32 v37, 31, v36
	v_lshl_add_u64 v[202:203], v[36:37], 2, s[16:17]
	global_load_dword v210, v[202:203], off
	global_load_dword v211, v[202:203], off offset:64
	global_load_dword v212, v[202:203], off offset:128
	global_load_dword v213, v[202:203], off offset:192
	global_load_dword v214, v[202:203], off offset:256
	global_load_dword v215, v[202:203], off offset:320
	global_load_dword v216, v[202:203], off offset:384
	global_load_dword v217, v[202:203], off offset:448
	s_waitcnt vmcnt(0)
	v_mul_f32_e32 v6, v6, v210
	v_mul_f32_e32 v7, v7, v210
	v_mul_f32_e32 v8, v8, v210
	v_mul_f32_e32 v9, v9, v210
	v_mul_f32_e32 v2, v2, v211
	v_mul_f32_e32 v3, v3, v211
	v_mul_f32_e32 v4, v4, v211
	v_mul_f32_e32 v5, v5, v211
	v_mul_f32_e32 v14, v14, v212
	v_mul_f32_e32 v15, v15, v212
	v_mul_f32_e32 v16, v16, v212
	v_mul_f32_e32 v17, v17, v212
	v_mul_f32_e32 v10, v10, v213
	v_mul_f32_e32 v11, v11, v213
	v_mul_f32_e32 v12, v12, v213
	v_mul_f32_e32 v13, v13, v213
	v_mul_f32_e32 v22, v22, v214
	v_mul_f32_e32 v23, v23, v214
	v_mul_f32_e32 v24, v24, v214
	v_mul_f32_e32 v25, v25, v214
	v_mul_f32_e32 v18, v18, v215
	v_mul_f32_e32 v19, v19, v215
	v_mul_f32_e32 v20, v20, v215
	v_mul_f32_e32 v21, v21, v215
	v_mul_f32_e32 v30, v30, v216
	v_mul_f32_e32 v31, v31, v216
	v_mul_f32_e32 v32, v32, v216
	v_mul_f32_e32 v33, v33, v216
	v_mul_f32_e32 v26, v26, v217
	v_mul_f32_e32 v27, v27, v217
	v_mul_f32_e32 v28, v28, v217
	v_mul_f32_e32 v29, v29, v217
